# gate-up GEMM epilogue hand-rewritten: 6-op silu*up chain (f32), 8-way interleave, no pk/mov/nop overhead; on top of v1
# speedup vs baseline: 1.0085x; 1.0085x over previous
; __device__ __forceinline__ u32x4 pack8(f32x4 a, f32x4 b) { u32x4 w; w.x = cvt_pk_bf16(a[0], a[1]); w.y = cvt_pk_bf16(a[2], a[3]); w.z = cvt_pk_bf16(b[0], b[1]); w.w = cvt_pk_bf16(b[2], b[3]); return w; }
; __device__ __forceinline__ void rstd8(const float* SS, int row0, int fq, float (&r)[2][4]) {
;     f32x4 v[2][4];
; #pragma unroll
;     for (int ai = 0; ai < 2; ++ai)
; #pragma unroll
;         for (int m = 0; m < 4; ++m) v[ai][m] = *(const f32x4*)(SS + (size_t)(row0 + ai * 128 + m * 16) * 16 + 4 * fq);
; #pragma unroll
;     for (int ai = 0; ai < 2; ++ai)
; #pragma unroll
;         for (int m = 0; m < 4; ++m) { float s = (v[ai][m][0] + v[ai][m][1]) + (v[ai][m][2] + v[ai][m][3]); s += __shfl_xor(s, 16); s += __shfl_xor(s, 32); r[ai][m] = rsqrtf(s * (1.0f / 1024.0f) + 1e-6f); }
; }
; __device__ __forceinline__ float sigm(float x) { return __builtin_amdgcn_rcpf(1.0f + __expf(-x)); }
;     __device__ __forceinline__ void operator()(const f32x4 (&acc)[2][2][4][2], const Unit& u, int wr, int wc, int fr_, int fq_) const {
;         int fr = fr_, fq = fq_; asm volatile("" : "+v"(fr), "+v"(fq));
;         float rs8[2][4]; rstd8(SS, u.pm * 256 + wr * 64 + fr, fq, rs8);
; #pragma unroll
;         for (int ai = 0; ai < 2; ++ai)
; #pragma unroll
;             for (int m = 0; m < 4; ++m) {
;                 const int row = u.pm * 256 + ai * 128 + wr * 64 + m * 16 + fr;
;                 const float rstd = rs8[ai][m];
;                 f32x4 o[2];
; #pragma unroll
;                 for (int n = 0; n < 2; ++n) { const f32x4 g = acc[ai][0][m][n] * rstd, up = acc[ai][1][m][n] * rstd;
; #pragma unroll
;                     for (int i = 0; i < 4; ++i) o[n][i] = g[i] * sigm(g[i]) * up[i]; }
;                 *(u32x4*)(ACT + (size_t)row * DFF + 128 * u.pn + 32 * wc + 8 * fq) = pack8(o[0], o[1]);
;             }
;     }
.LBB0_50:
	s_lshl_b32 s0, s0, 8
	s_add_i32 s0, s0, s68
	v_add_u32_e32 v168, s0, v184
	v_lshlrev_b32_e32 v169, 4, v185
	v_lshl_add_u32 v169, v168, 6, v169
	global_load_dwordx4 v[130:133], v169, s[46:47]
	global_load_dwordx4 v[134:137], v169, s[46:47] offset:1024
	global_load_dwordx4 v[138:141], v169, s[46:47] offset:2048
	global_load_dwordx4 v[142:145], v169, s[46:47] offset:3072
	v_add_u32_e32 v169, 0x2000, v169
	global_load_dwordx4 v[146:149], v169, s[46:47]
	global_load_dwordx4 v[150:153], v169, s[46:47] offset:1024
	global_load_dwordx4 v[154:157], v169, s[46:47] offset:2048
	global_load_dwordx4 v[158:161], v169, s[46:47] offset:3072
	v_xor_b32_e32 v170, 16, v203
	v_xor_b32_e32 v171, 32, v203
	v_lshlrev_b32_e32 v170, 2, v170
	v_lshlrev_b32_e32 v171, 2, v171
	s_movk_i32 s21, 0x1600
	v_readlane_b32 s30, v253, 13
	v_readlane_b32 s31, v253, 14
	s_lshl_b32 s0, s44, 8
	s_add_i32 s0, s0, s24
	v_mul_lo_u32 v172, v168, s21
	v_lshl_add_u32 v173, v185, 4, s0
	v_add_u32_e32 v172, v172, v173
	s_mov_b32 s0, 0x3a800000
	v_mov_b32_e32 v173, 0x358637bd
	s_waitcnt vmcnt(0)
	v_add_f32_e32 v130, v130, v131
	v_add_f32_e32 v132, v132, v133
	v_add_f32_e32 v134, v134, v135
	v_add_f32_e32 v136, v136, v137
	v_add_f32_e32 v138, v138, v139
	v_add_f32_e32 v140, v140, v141
	v_add_f32_e32 v142, v142, v143
	v_add_f32_e32 v144, v144, v145
	v_add_f32_e32 v146, v146, v147
	v_add_f32_e32 v148, v148, v149
	v_add_f32_e32 v150, v150, v151
	v_add_f32_e32 v152, v152, v153
	v_add_f32_e32 v154, v154, v155
	v_add_f32_e32 v156, v156, v157
	v_add_f32_e32 v158, v158, v159
	v_add_f32_e32 v160, v160, v161
	v_add_f32_e32 v130, v130, v132
	v_add_f32_e32 v134, v134, v136
	v_add_f32_e32 v138, v138, v140
	v_add_f32_e32 v142, v142, v144
	v_add_f32_e32 v146, v146, v148
	v_add_f32_e32 v150, v150, v152
	v_add_f32_e32 v154, v154, v156
	v_add_f32_e32 v158, v158, v160
	ds_bpermute_b32 v131, v170, v130
	ds_bpermute_b32 v135, v170, v134
	ds_bpermute_b32 v139, v170, v138
	ds_bpermute_b32 v143, v170, v142
	ds_bpermute_b32 v147, v170, v146
	ds_bpermute_b32 v151, v170, v150
	ds_bpermute_b32 v155, v170, v154
	ds_bpermute_b32 v159, v170, v158
	s_waitcnt lgkmcnt(0)
	v_add_f32_e32 v130, v130, v131
	v_add_f32_e32 v134, v134, v135
	v_add_f32_e32 v138, v138, v139
	v_add_f32_e32 v142, v142, v143
	v_add_f32_e32 v146, v146, v147
	v_add_f32_e32 v150, v150, v151
	v_add_f32_e32 v154, v154, v155
	v_add_f32_e32 v158, v158, v159
	ds_bpermute_b32 v131, v171, v130
	ds_bpermute_b32 v135, v171, v134
	ds_bpermute_b32 v139, v171, v138
	ds_bpermute_b32 v143, v171, v142
	ds_bpermute_b32 v147, v171, v146
	ds_bpermute_b32 v151, v171, v150
	ds_bpermute_b32 v155, v171, v154
	ds_bpermute_b32 v159, v171, v158
	s_waitcnt lgkmcnt(0)
	v_add_f32_e32 v130, v130, v131
	v_add_f32_e32 v134, v134, v135
	v_add_f32_e32 v138, v138, v139
	v_add_f32_e32 v142, v142, v143
	v_add_f32_e32 v146, v146, v147
	v_add_f32_e32 v150, v150, v151
	v_add_f32_e32 v154, v154, v155
	v_add_f32_e32 v158, v158, v159
	v_fma_f32 v130, v130, s0, v173
	v_fma_f32 v134, v134, s0, v173
	v_fma_f32 v138, v138, s0, v173
	v_fma_f32 v142, v142, s0, v173
	v_fma_f32 v146, v146, s0, v173
	v_fma_f32 v150, v150, s0, v173
	v_fma_f32 v154, v154, s0, v173
	v_fma_f32 v158, v158, s0, v173
	v_rsq_f32_e32 v131, v130
	v_rsq_f32_e32 v135, v134
	v_rsq_f32_e32 v139, v138
	v_rsq_f32_e32 v143, v142
	v_rsq_f32_e32 v147, v146
	v_rsq_f32_e32 v151, v150
	v_rsq_f32_e32 v155, v154
	v_rsq_f32_e32 v159, v158
	v_mul_f32_e32 v131, 0xbfb8aa3b, v131
	v_mul_f32_e32 v135, 0xbfb8aa3b, v135
	v_mul_f32_e32 v139, 0xbfb8aa3b, v139
	v_mul_f32_e32 v143, 0xbfb8aa3b, v143
	v_mul_f32_e32 v147, 0xbfb8aa3b, v147
	v_mul_f32_e32 v151, 0xbfb8aa3b, v151
	v_mul_f32_e32 v155, 0xbfb8aa3b, v155
	v_mul_f32_e32 v159, 0xbfb8aa3b, v159
	v_mul_f32_e32 v126, v122, v126
	v_mul_f32_e32 v127, v123, v127
	v_mul_f32_e32 v128, v124, v128
	v_mul_f32_e32 v129, v125, v129
	v_mul_f32_e32 v118, v114, v118
	v_mul_f32_e32 v119, v115, v119
	v_mul_f32_e32 v120, v116, v120
	v_mul_f32_e32 v121, v117, v121
	v_mul_f32_e32 v122, v131, v122
	v_mul_f32_e32 v123, v131, v123
	v_mul_f32_e32 v124, v131, v124
	v_mul_f32_e32 v125, v131, v125
	v_mul_f32_e32 v114, v131, v114
	v_mul_f32_e32 v115, v131, v115
	v_mul_f32_e32 v116, v131, v116
	v_mul_f32_e32 v117, v131, v117
	v_exp_f32_e32 v122, v122
	v_exp_f32_e32 v123, v123
	v_exp_f32_e32 v124, v124
	v_exp_f32_e32 v125, v125
	v_exp_f32_e32 v114, v114
	v_exp_f32_e32 v115, v115
	v_exp_f32_e32 v116, v116
	v_exp_f32_e32 v117, v117
	v_fma_f32 v122, v122, v130, v130
	v_fma_f32 v123, v123, v130, v130
	v_fma_f32 v124, v124, v130, v130
	v_fma_f32 v125, v125, v130, v130
	v_fma_f32 v114, v114, v130, v130
	v_fma_f32 v115, v115, v130, v130
	v_fma_f32 v116, v116, v130, v130
	v_fma_f32 v117, v117, v130, v130
	v_rcp_f32_e32 v122, v122
	v_rcp_f32_e32 v123, v123
	v_rcp_f32_e32 v124, v124
	v_rcp_f32_e32 v125, v125
	v_rcp_f32_e32 v114, v114
	v_rcp_f32_e32 v115, v115
	v_rcp_f32_e32 v116, v116
	v_rcp_f32_e32 v117, v117
	v_mul_f32_e32 v126, v126, v122
	v_mul_f32_e32 v127, v127, v123
	v_mul_f32_e32 v128, v128, v124
	v_mul_f32_e32 v129, v129, v125
	v_mul_f32_e32 v118, v118, v114
	v_mul_f32_e32 v119, v119, v115
	v_mul_f32_e32 v120, v120, v116
	v_mul_f32_e32 v121, v121, v117
	v_cvt_pk_bf16_f32 v122, v126, v127
	v_cvt_pk_bf16_f32 v123, v128, v129
	v_cvt_pk_bf16_f32 v124, v118, v119
	v_cvt_pk_bf16_f32 v125, v120, v121
	global_store_dwordx4 v172, v[122:125], s[30:31]
	v_add_u32_e32 v172, 0x16000, v172
	v_mul_f32_e32 v110, v106, v110
	v_mul_f32_e32 v111, v107, v111
	v_mul_f32_e32 v112, v108, v112
	v_mul_f32_e32 v113, v109, v113
	v_mul_f32_e32 v102, v98, v102
	v_mul_f32_e32 v103, v99, v103
	v_mul_f32_e32 v104, v100, v104
	v_mul_f32_e32 v105, v101, v105
; __device__ __forceinline__ float sigm(float x) { return __builtin_amdgcn_rcpf(1.0f + __expf(-x)); }
; __device__ __forceinline__ u32x4 pack8(f32x4 a, f32x4 b) { u32x4 w; w.x = cvt_pk_bf16(a[0], a[1]); w.y = cvt_pk_bf16(a[2], a[3]); w.z = cvt_pk_bf16(b[0], b[1]); w.w = cvt_pk_bf16(b[2], b[3]); return w; }
;     __device__ __forceinline__ void operator()(const f32x4 (&acc)[2][2][4][2], const Unit& u, int wr, int wc, int fr_, int fq_) const {
;         int fr = fr_, fq = fq_; asm volatile("" : "+v"(fr), "+v"(fq));
;         float rs8[2][4]; rstd8(SS, u.pm * 256 + wr * 64 + fr, fq, rs8);
; #pragma unroll
;         for (int ai = 0; ai < 2; ++ai)
; #pragma unroll
;             for (int m = 0; m < 4; ++m) {
;                 const int row = u.pm * 256 + ai * 128 + wr * 64 + m * 16 + fr;
;                 const float rstd = rs8[ai][m];
;                 f32x4 o[2];
; #pragma unroll
;                 for (int n = 0; n < 2; ++n) { const f32x4 g = acc[ai][0][m][n] * rstd, up = acc[ai][1][m][n] * rstd;
; #pragma unroll
;                     for (int i = 0; i < 4; ++i) o[n][i] = g[i] * sigm(g[i]) * up[i]; }
;                 *(u32x4*)(ACT + (size_t)row * DFF + 128 * u.pn + 32 * wc + 8 * fq) = pack8(o[0], o[1]);
;             }
;     }
	v_mul_f32_e32 v106, v135, v106
	v_mul_f32_e32 v107, v135, v107
	v_mul_f32_e32 v108, v135, v108
	v_mul_f32_e32 v109, v135, v109
	v_mul_f32_e32 v98, v135, v98
	v_mul_f32_e32 v99, v135, v99
	v_mul_f32_e32 v100, v135, v100
	v_mul_f32_e32 v101, v135, v101
	v_exp_f32_e32 v106, v106
	v_exp_f32_e32 v107, v107
	v_exp_f32_e32 v108, v108
	v_exp_f32_e32 v109, v109
	v_exp_f32_e32 v98, v98
	v_exp_f32_e32 v99, v99
	v_exp_f32_e32 v100, v100
	v_exp_f32_e32 v101, v101
	v_fma_f32 v106, v106, v134, v134
	v_fma_f32 v107, v107, v134, v134
	v_fma_f32 v108, v108, v134, v134
	v_fma_f32 v109, v109, v134, v134
	v_fma_f32 v98, v98, v134, v134
	v_fma_f32 v99, v99, v134, v134
	v_fma_f32 v100, v100, v134, v134
	v_fma_f32 v101, v101, v134, v134
	v_rcp_f32_e32 v106, v106
	v_rcp_f32_e32 v107, v107
	v_rcp_f32_e32 v108, v108
	v_rcp_f32_e32 v109, v109
	v_rcp_f32_e32 v98, v98
	v_rcp_f32_e32 v99, v99
	v_rcp_f32_e32 v100, v100
	v_rcp_f32_e32 v101, v101
	v_mul_f32_e32 v110, v110, v106
	v_mul_f32_e32 v111, v111, v107
	v_mul_f32_e32 v112, v112, v108
	v_mul_f32_e32 v113, v113, v109
	v_mul_f32_e32 v102, v102, v98
	v_mul_f32_e32 v103, v103, v99
	v_mul_f32_e32 v104, v104, v100
	v_mul_f32_e32 v105, v105, v101
	v_cvt_pk_bf16_f32 v106, v110, v111
	v_cvt_pk_bf16_f32 v107, v112, v113
	v_cvt_pk_bf16_f32 v108, v102, v103
	v_cvt_pk_bf16_f32 v109, v104, v105
	global_store_dwordx4 v172, v[106:109], s[30:31]
	v_add_u32_e32 v172, 0x16000, v172
	v_mul_f32_e32 v94, v90, v94
	v_mul_f32_e32 v95, v91, v95
	v_mul_f32_e32 v96, v92, v96
	v_mul_f32_e32 v97, v93, v97
	v_mul_f32_e32 v86, v82, v86
	v_mul_f32_e32 v87, v83, v87
	v_mul_f32_e32 v88, v84, v88
	v_mul_f32_e32 v89, v85, v89
	v_mul_f32_e32 v90, v139, v90
	v_mul_f32_e32 v91, v139, v91
	v_mul_f32_e32 v92, v139, v92
	v_mul_f32_e32 v93, v139, v93
	v_mul_f32_e32 v82, v139, v82
	v_mul_f32_e32 v83, v139, v83
	v_mul_f32_e32 v84, v139, v84
	v_mul_f32_e32 v85, v139, v85
	v_exp_f32_e32 v90, v90
	v_exp_f32_e32 v91, v91
	v_exp_f32_e32 v92, v92
	v_exp_f32_e32 v93, v93
	v_exp_f32_e32 v82, v82
	v_exp_f32_e32 v83, v83
	v_exp_f32_e32 v84, v84
	v_exp_f32_e32 v85, v85
	v_fma_f32 v90, v90, v138, v138
	v_fma_f32 v91, v91, v138, v138
	v_fma_f32 v92, v92, v138, v138
	v_fma_f32 v93, v93, v138, v138
	v_fma_f32 v82, v82, v138, v138
	v_fma_f32 v83, v83, v138, v138
	v_fma_f32 v84, v84, v138, v138
	v_fma_f32 v85, v85, v138, v138
	v_rcp_f32_e32 v90, v90
	v_rcp_f32_e32 v91, v91
	v_rcp_f32_e32 v92, v92
	v_rcp_f32_e32 v93, v93
	v_rcp_f32_e32 v82, v82
	v_rcp_f32_e32 v83, v83
	v_rcp_f32_e32 v84, v84
	v_rcp_f32_e32 v85, v85
	v_mul_f32_e32 v94, v94, v90
	v_mul_f32_e32 v95, v95, v91
	v_mul_f32_e32 v96, v96, v92
	v_mul_f32_e32 v97, v97, v93
	v_mul_f32_e32 v86, v86, v82
	v_mul_f32_e32 v87, v87, v83
	v_mul_f32_e32 v88, v88, v84
	v_mul_f32_e32 v89, v89, v85
	v_cvt_pk_bf16_f32 v90, v94, v95
	v_cvt_pk_bf16_f32 v91, v96, v97
	v_cvt_pk_bf16_f32 v92, v86, v87
	v_cvt_pk_bf16_f32 v93, v88, v89
	global_store_dwordx4 v172, v[90:93], s[30:31]
	v_add_u32_e32 v172, 0x16000, v172
	v_mul_f32_e32 v78, v74, v78
	v_mul_f32_e32 v79, v75, v79
	v_mul_f32_e32 v80, v76, v80
	v_mul_f32_e32 v81, v77, v81
	v_mul_f32_e32 v70, v66, v70
	v_mul_f32_e32 v71, v67, v71
	v_mul_f32_e32 v72, v68, v72
	v_mul_f32_e32 v73, v69, v73
	v_mul_f32_e32 v74, v143, v74
	v_mul_f32_e32 v75, v143, v75
	v_mul_f32_e32 v76, v143, v76
	v_mul_f32_e32 v77, v143, v77
	v_mul_f32_e32 v66, v143, v66
	v_mul_f32_e32 v67, v143, v67
	v_mul_f32_e32 v68, v143, v68
	v_mul_f32_e32 v69, v143, v69
	v_exp_f32_e32 v74, v74
	v_exp_f32_e32 v75, v75
	v_exp_f32_e32 v76, v76
	v_exp_f32_e32 v77, v77
	v_exp_f32_e32 v66, v66
	v_exp_f32_e32 v67, v67
	v_exp_f32_e32 v68, v68
	v_exp_f32_e32 v69, v69
	v_fma_f32 v74, v74, v142, v142
	v_fma_f32 v75, v75, v142, v142
	v_fma_f32 v76, v76, v142, v142
	v_fma_f32 v77, v77, v142, v142
	v_fma_f32 v66, v66, v142, v142
	v_fma_f32 v67, v67, v142, v142
	v_fma_f32 v68, v68, v142, v142
	v_fma_f32 v69, v69, v142, v142
	v_rcp_f32_e32 v74, v74
	v_rcp_f32_e32 v75, v75
	v_rcp_f32_e32 v76, v76
	v_rcp_f32_e32 v77, v77
	v_rcp_f32_e32 v66, v66
	v_rcp_f32_e32 v67, v67
	v_rcp_f32_e32 v68, v68
	v_rcp_f32_e32 v69, v69
	v_mul_f32_e32 v78, v78, v74
	v_mul_f32_e32 v79, v79, v75
	v_mul_f32_e32 v80, v80, v76
	v_mul_f32_e32 v81, v81, v77
	v_mul_f32_e32 v70, v70, v66
	v_mul_f32_e32 v71, v71, v67
	v_mul_f32_e32 v72, v72, v68
	v_mul_f32_e32 v73, v73, v69
	v_cvt_pk_bf16_f32 v74, v78, v79
	v_cvt_pk_bf16_f32 v75, v80, v81
	v_cvt_pk_bf16_f32 v76, v70, v71
	v_cvt_pk_bf16_f32 v77, v72, v73
	global_store_dwordx4 v172, v[74:77], s[30:31]
	v_add_u32_e32 v172, 0x6e000, v172
	v_mul_f32_e32 v62, v58, v62
	v_mul_f32_e32 v63, v59, v63
	v_mul_f32_e32 v64, v60, v64
	v_mul_f32_e32 v65, v61, v65
	v_mul_f32_e32 v54, v50, v54
	v_mul_f32_e32 v55, v51, v55
	v_mul_f32_e32 v56, v52, v56
	v_mul_f32_e32 v57, v53, v57
	v_mul_f32_e32 v58, v147, v58
	v_mul_f32_e32 v59, v147, v59
	v_mul_f32_e32 v60, v147, v60
	v_mul_f32_e32 v61, v147, v61
	v_mul_f32_e32 v50, v147, v50
	v_mul_f32_e32 v51, v147, v51
	v_mul_f32_e32 v52, v147, v52
	v_mul_f32_e32 v53, v147, v53
	v_exp_f32_e32 v58, v58
	v_exp_f32_e32 v59, v59
	v_exp_f32_e32 v60, v60
	v_exp_f32_e32 v61, v61
	v_exp_f32_e32 v50, v50
	v_exp_f32_e32 v51, v51
	v_exp_f32_e32 v52, v52
	v_exp_f32_e32 v53, v53
	v_fma_f32 v58, v58, v146, v146
	v_fma_f32 v59, v59, v146, v146
	v_fma_f32 v60, v60, v146, v146
	v_fma_f32 v61, v61, v146, v146
	v_fma_f32 v50, v50, v146, v146
	v_fma_f32 v51, v51, v146, v146
	v_fma_f32 v52, v52, v146, v146
	v_fma_f32 v53, v53, v146, v146
; __device__ __forceinline__ float sigm(float x) { return __builtin_amdgcn_rcpf(1.0f + __expf(-x)); }
; __device__ __forceinline__ u32x4 pack8(f32x4 a, f32x4 b) { u32x4 w; w.x = cvt_pk_bf16(a[0], a[1]); w.y = cvt_pk_bf16(a[2], a[3]); w.z = cvt_pk_bf16(b[0], b[1]); w.w = cvt_pk_bf16(b[2], b[3]); return w; }
;     __device__ __forceinline__ void operator()(const f32x4 (&acc)[2][2][4][2], const Unit& u, int wr, int wc, int fr_, int fq_) const {
;         int fr = fr_, fq = fq_; asm volatile("" : "+v"(fr), "+v"(fq));
;         float rs8[2][4]; rstd8(SS, u.pm * 256 + wr * 64 + fr, fq, rs8);
; #pragma unroll
;         for (int ai = 0; ai < 2; ++ai)
; #pragma unroll
;             for (int m = 0; m < 4; ++m) {
;                 const int row = u.pm * 256 + ai * 128 + wr * 64 + m * 16 + fr;
;                 const float rstd = rs8[ai][m];
;                 f32x4 o[2];
; #pragma unroll
;                 for (int n = 0; n < 2; ++n) { const f32x4 g = acc[ai][0][m][n] * rstd, up = acc[ai][1][m][n] * rstd;
; #pragma unroll
;                     for (int i = 0; i < 4; ++i) o[n][i] = g[i] * sigm(g[i]) * up[i]; }
;                 *(u32x4*)(ACT + (size_t)row * DFF + 128 * u.pn + 32 * wc + 8 * fq) = pack8(o[0], o[1]);
;             }
;     }
	v_rcp_f32_e32 v58, v58
	v_rcp_f32_e32 v59, v59
	v_rcp_f32_e32 v60, v60
	v_rcp_f32_e32 v61, v61
	v_rcp_f32_e32 v50, v50
	v_rcp_f32_e32 v51, v51
	v_rcp_f32_e32 v52, v52
	v_rcp_f32_e32 v53, v53
	v_mul_f32_e32 v62, v62, v58
	v_mul_f32_e32 v63, v63, v59
	v_mul_f32_e32 v64, v64, v60
	v_mul_f32_e32 v65, v65, v61
	v_mul_f32_e32 v54, v54, v50
	v_mul_f32_e32 v55, v55, v51
	v_mul_f32_e32 v56, v56, v52
	v_mul_f32_e32 v57, v57, v53
	v_cvt_pk_bf16_f32 v58, v62, v63
	v_cvt_pk_bf16_f32 v59, v64, v65
	v_cvt_pk_bf16_f32 v60, v54, v55
	v_cvt_pk_bf16_f32 v61, v56, v57
	global_store_dwordx4 v172, v[58:61], s[30:31]
	v_add_u32_e32 v172, 0x16000, v172
	v_mul_f32_e32 v46, v42, v46
	v_mul_f32_e32 v47, v43, v47
	v_mul_f32_e32 v48, v44, v48
	v_mul_f32_e32 v49, v45, v49
	v_mul_f32_e32 v38, v34, v38
	v_mul_f32_e32 v39, v35, v39
	v_mul_f32_e32 v40, v36, v40
	v_mul_f32_e32 v41, v37, v41
	v_mul_f32_e32 v42, v151, v42
	v_mul_f32_e32 v43, v151, v43
	v_mul_f32_e32 v44, v151, v44
	v_mul_f32_e32 v45, v151, v45
	v_mul_f32_e32 v34, v151, v34
	v_mul_f32_e32 v35, v151, v35
	v_mul_f32_e32 v36, v151, v36
	v_mul_f32_e32 v37, v151, v37
	v_exp_f32_e32 v42, v42
	v_exp_f32_e32 v43, v43
	v_exp_f32_e32 v44, v44
	v_exp_f32_e32 v45, v45
	v_exp_f32_e32 v34, v34
	v_exp_f32_e32 v35, v35
	v_exp_f32_e32 v36, v36
	v_exp_f32_e32 v37, v37
	v_fma_f32 v42, v42, v150, v150
	v_fma_f32 v43, v43, v150, v150
	v_fma_f32 v44, v44, v150, v150
	v_fma_f32 v45, v45, v150, v150
	v_fma_f32 v34, v34, v150, v150
	v_fma_f32 v35, v35, v150, v150
	v_fma_f32 v36, v36, v150, v150
	v_fma_f32 v37, v37, v150, v150
	v_rcp_f32_e32 v42, v42
	v_rcp_f32_e32 v43, v43
	v_rcp_f32_e32 v44, v44
	v_rcp_f32_e32 v45, v45
	v_rcp_f32_e32 v34, v34
	v_rcp_f32_e32 v35, v35
	v_rcp_f32_e32 v36, v36
	v_rcp_f32_e32 v37, v37
	v_mul_f32_e32 v46, v46, v42
	v_mul_f32_e32 v47, v47, v43
	v_mul_f32_e32 v48, v48, v44
	v_mul_f32_e32 v49, v49, v45
	v_mul_f32_e32 v38, v38, v34
	v_mul_f32_e32 v39, v39, v35
	v_mul_f32_e32 v40, v40, v36
	v_mul_f32_e32 v41, v41, v37
	v_cvt_pk_bf16_f32 v42, v46, v47
	v_cvt_pk_bf16_f32 v43, v48, v49
	v_cvt_pk_bf16_f32 v44, v38, v39
	v_cvt_pk_bf16_f32 v45, v40, v41
	global_store_dwordx4 v172, v[42:45], s[30:31]
	v_add_u32_e32 v172, 0x16000, v172
	v_mul_f32_e32 v30, v26, v30
	v_mul_f32_e32 v31, v27, v31
	v_mul_f32_e32 v32, v28, v32
	v_mul_f32_e32 v33, v29, v33
	v_mul_f32_e32 v22, v18, v22
	v_mul_f32_e32 v23, v19, v23
	v_mul_f32_e32 v24, v20, v24
	v_mul_f32_e32 v25, v21, v25
	v_mul_f32_e32 v26, v155, v26
	v_mul_f32_e32 v27, v155, v27
	v_mul_f32_e32 v28, v155, v28
	v_mul_f32_e32 v29, v155, v29
	v_mul_f32_e32 v18, v155, v18
	v_mul_f32_e32 v19, v155, v19
	v_mul_f32_e32 v20, v155, v20
	v_mul_f32_e32 v21, v155, v21
	v_exp_f32_e32 v26, v26
	v_exp_f32_e32 v27, v27
	v_exp_f32_e32 v28, v28
	v_exp_f32_e32 v29, v29
	v_exp_f32_e32 v18, v18
	v_exp_f32_e32 v19, v19
	v_exp_f32_e32 v20, v20
	v_exp_f32_e32 v21, v21
	v_fma_f32 v26, v26, v154, v154
	v_fma_f32 v27, v27, v154, v154
	v_fma_f32 v28, v28, v154, v154
	v_fma_f32 v29, v29, v154, v154
	v_fma_f32 v18, v18, v154, v154
	v_fma_f32 v19, v19, v154, v154
	v_fma_f32 v20, v20, v154, v154
	v_fma_f32 v21, v21, v154, v154
	v_rcp_f32_e32 v26, v26
	v_rcp_f32_e32 v27, v27
	v_rcp_f32_e32 v28, v28
	v_rcp_f32_e32 v29, v29
	v_rcp_f32_e32 v18, v18
	v_rcp_f32_e32 v19, v19
	v_rcp_f32_e32 v20, v20
	v_rcp_f32_e32 v21, v21
	v_mul_f32_e32 v30, v30, v26
	v_mul_f32_e32 v31, v31, v27
	v_mul_f32_e32 v32, v32, v28
	v_mul_f32_e32 v33, v33, v29
	v_mul_f32_e32 v22, v22, v18
	v_mul_f32_e32 v23, v23, v19
	v_mul_f32_e32 v24, v24, v20
	v_mul_f32_e32 v25, v25, v21
	v_cvt_pk_bf16_f32 v26, v30, v31
	v_cvt_pk_bf16_f32 v27, v32, v33
	v_cvt_pk_bf16_f32 v28, v22, v23
	v_cvt_pk_bf16_f32 v29, v24, v25
	global_store_dwordx4 v172, v[26:29], s[30:31]
	v_add_u32_e32 v172, 0x16000, v172
	v_mul_f32_e32 v14, v10, v14
	v_mul_f32_e32 v15, v11, v15
	v_mul_f32_e32 v16, v12, v16
	v_mul_f32_e32 v17, v13, v17
	v_mul_f32_e32 v6, v2, v6
	v_mul_f32_e32 v7, v3, v7
	v_mul_f32_e32 v8, v4, v8
	v_mul_f32_e32 v9, v5, v9
	v_mul_f32_e32 v10, v159, v10
	v_mul_f32_e32 v11, v159, v11
	v_mul_f32_e32 v12, v159, v12
	v_mul_f32_e32 v13, v159, v13
	v_mul_f32_e32 v2, v159, v2
	v_mul_f32_e32 v3, v159, v3
	v_mul_f32_e32 v4, v159, v4
	v_mul_f32_e32 v5, v159, v5
	v_exp_f32_e32 v10, v10
	v_exp_f32_e32 v11, v11
	v_exp_f32_e32 v12, v12
	v_exp_f32_e32 v13, v13
	v_exp_f32_e32 v2, v2
	v_exp_f32_e32 v3, v3
	v_exp_f32_e32 v4, v4
	v_exp_f32_e32 v5, v5
	v_fma_f32 v10, v10, v158, v158
	v_fma_f32 v11, v11, v158, v158
	v_fma_f32 v12, v12, v158, v158
	v_fma_f32 v13, v13, v158, v158
	v_fma_f32 v2, v2, v158, v158
	v_fma_f32 v3, v3, v158, v158
	v_fma_f32 v4, v4, v158, v158
	v_fma_f32 v5, v5, v158, v158
	v_rcp_f32_e32 v10, v10
	v_rcp_f32_e32 v11, v11
	v_rcp_f32_e32 v12, v12
	v_rcp_f32_e32 v13, v13
	v_rcp_f32_e32 v2, v2
	v_rcp_f32_e32 v3, v3
	v_rcp_f32_e32 v4, v4
	v_rcp_f32_e32 v5, v5
	v_mul_f32_e32 v14, v14, v10
	v_mul_f32_e32 v15, v15, v11
	v_mul_f32_e32 v16, v16, v12
	v_mul_f32_e32 v17, v17, v13
	v_mul_f32_e32 v6, v6, v2
	v_mul_f32_e32 v7, v7, v3
	v_mul_f32_e32 v8, v8, v4
	v_mul_f32_e32 v9, v9, v5
	v_cvt_pk_bf16_f32 v10, v14, v15
	v_cvt_pk_bf16_f32 v11, v16, v17
	v_cvt_pk_bf16_f32 v12, v6, v7
	v_cvt_pk_bf16_f32 v13, v8, v9
	global_store_dwordx4 v172, v[10:13], s[30:31]
	s_andn2_b64 vcc, exec, s[38:39]
	s_mov_b64 s[0:1], -1
	s_cbranch_vccnz .LBB0_43
	v_readlane_b32 s0, v255, 45
	v_readlane_b32 s1, v255, 46
	s_andn2_b64 vcc, exec, s[0:1]
	s_cbranch_vccnz .LBB0_42
	s_barrier
	s_branch .LBB0_42
